# scan loader waves run at priority 3 only while issuing their 14 record prefetch loads (compute waves stay at 2)
# baseline (speedup 1.0000x reference)
; DI void gdn_scan(const Args& a, int l, int bh, LAS unsigned char* lds, const int tidx, const bool nostore) {
;     ...
;         for (int n2 = 0; n2 < 64; n2 += 2) {
;             LOADER_ITER(n2, pfa, pfb);
;             LOADER_ITER(n2 + 1, pfb, pfa);
;         }
.LBB0_367:
	s_cmp_gt_u32 s6, 61
	s_cselect_b64 s[4:5], -1, 0
	s_and_b64 vcc, exec, s[4:5]
	v_lshl_add_u64 v[172:173], v[114:115], 0, s[94:95]
	v_lshl_add_u64 v[170:171], v[116:117], 0, s[94:95]
	v_lshl_add_u64 v[168:169], v[118:119], 0, s[94:95]
	v_lshl_add_u64 v[166:167], v[120:121], 0, s[94:95]
	v_lshl_add_u64 v[164:165], v[122:123], 0, s[94:95]
	v_lshl_add_u64 v[160:161], v[124:125], 0, s[94:95]
	v_lshl_add_u64 v[158:159], v[126:127], 0, s[94:95]
	v_lshl_add_u64 v[156:157], v[128:129], 0, s[94:95]
	v_lshl_add_u64 v[154:155], v[130:131], 0, s[94:95]
	v_lshl_add_u64 v[152:153], v[132:133], 0, s[94:95]
	v_lshl_add_u64 v[150:151], v[134:135], 0, s[94:95]
	v_lshl_add_u64 v[148:149], v[136:137], 0, s[94:95]
	v_lshl_add_u64 v[146:147], v[138:139], 0, s[94:95]
	v_lshl_add_u64 v[144:145], v[140:141], 0, s[94:95]
	s_cbranch_vccnz .LBB0_369
	s_setprio 3
	v_add_co_u32_e32 v0, vcc, 0x15538000, v172
	s_nop 1
	v_addc_co_u32_e32 v1, vcc, 0, v173, vcc
	v_add_co_u32_e32 v4, vcc, 0x15538000, v170
	global_load_dwordx4 v[0:3], v[0:1], off
	s_nop 0
	v_addc_co_u32_e32 v5, vcc, 0, v171, vcc
	v_add_co_u32_e32 v8, vcc, 0x15538000, v168
	global_load_dwordx4 v[4:7], v[4:5], off
	s_nop 0
	v_addc_co_u32_e32 v9, vcc, 0, v169, vcc
	v_add_co_u32_e32 v12, vcc, 0x15538000, v166
	global_load_dwordx4 v[8:11], v[8:9], off
	s_nop 0
	v_addc_co_u32_e32 v13, vcc, 0, v167, vcc
	v_add_co_u32_e32 v16, vcc, 0x15538000, v164
	global_load_dwordx4 v[12:15], v[12:13], off
	s_nop 0
	v_addc_co_u32_e32 v17, vcc, 0, v165, vcc
	v_add_co_u32_e32 v20, vcc, 0x15538000, v160
	global_load_dwordx4 v[16:19], v[16:17], off
	s_nop 0
	v_addc_co_u32_e32 v21, vcc, 0, v161, vcc
	v_add_co_u32_e32 v24, vcc, 0x15538000, v158
	global_load_dwordx4 v[20:23], v[20:21], off
	s_nop 0
	v_addc_co_u32_e32 v25, vcc, 0, v159, vcc
	v_add_co_u32_e32 v28, vcc, 0x15538000, v156
	global_load_dwordx4 v[24:27], v[24:25], off
	s_nop 0
	v_addc_co_u32_e32 v29, vcc, 0, v157, vcc
	v_add_co_u32_e32 v32, vcc, 0x15538000, v154
	global_load_dwordx4 v[28:31], v[28:29], off
	s_nop 0
	v_addc_co_u32_e32 v33, vcc, 0, v155, vcc
	v_add_co_u32_e32 v36, vcc, 0x15538000, v152
	global_load_dwordx4 v[32:35], v[32:33], off
	s_nop 0
	v_addc_co_u32_e32 v37, vcc, 0, v153, vcc
	v_add_co_u32_e32 v40, vcc, 0x15538000, v150
	global_load_dwordx4 v[36:39], v[36:37], off
	s_nop 0
	v_addc_co_u32_e32 v41, vcc, 0, v151, vcc
	v_add_co_u32_e32 v44, vcc, 0x15538000, v148
	global_load_dwordx4 v[40:43], v[40:41], off
	s_nop 0
	v_addc_co_u32_e32 v45, vcc, 0, v149, vcc
	v_add_co_u32_e32 v48, vcc, 0x15538000, v146
	global_load_dwordx4 v[44:47], v[44:45], off
	s_nop 0
	v_addc_co_u32_e32 v49, vcc, 0, v147, vcc
	v_add_co_u32_e32 v52, vcc, 0x15538000, v144
	global_load_dwordx4 v[48:51], v[48:49], off
	s_nop 0
	v_addc_co_u32_e32 v53, vcc, 0, v145, vcc
	global_load_dwordx4 v[52:55], v[52:53], off
	s_setprio 0
	s_and_b64 vcc, exec, s[0:1]
	s_cbranch_vccnz .Lldr_even_A27
	s_waitcnt vmcnt(31)
	ds_write_b128 v174, v[56:59] offset:57344
	s_waitcnt vmcnt(30)
	ds_write_b128 v174, v[60:63] offset:61440
	s_waitcnt vmcnt(29)
	ds_write_b128 v175, v[64:67] offset:8192
	s_waitcnt vmcnt(28)
	ds_write_b128 v175, v[68:71] offset:12288
	s_waitcnt vmcnt(27)
	ds_write_b128 v175, v[72:75] offset:16384
	s_waitcnt vmcnt(26)
	ds_write_b128 v175, v[76:79] offset:20480
	s_waitcnt vmcnt(25)
	ds_write_b128 v175, v[80:83] offset:24576
	s_waitcnt vmcnt(24)
	ds_write_b128 v175, v[84:87] offset:28672
	s_waitcnt vmcnt(23)
	ds_write_b128 v175, v[88:91] offset:32768
	s_waitcnt vmcnt(22)
	ds_write_b128 v175, v[92:95] offset:36864
	s_waitcnt vmcnt(21)
	ds_write_b128 v175, v[96:99] offset:40960
	s_waitcnt vmcnt(20)
	ds_write_b128 v175, v[100:103] offset:45056
	s_waitcnt vmcnt(19)
	ds_write_b128 v175, v[104:107] offset:49152
	s_waitcnt vmcnt(18)
	ds_write_b128 v175, v[108:111] offset:53248
	s_branch .Lldr_even_wr_done

; DI void gdn_scan(const Args& a, int l, int bh, LAS unsigned char* lds, const int tidx, const bool nostore) {
;     ...
;         for (int n2 = 0; n2 < 64; n2 += 2) {
;             LOADER_ITER(n2, pfa, pfb);
;             LOADER_ITER(n2 + 1, pfb, pfa);
;         }
.LBB0_373:
	s_setprio 3
	v_add_co_u32_e32 v56, vcc, 0x15546000, v172
	s_nop 1
	v_addc_co_u32_e32 v57, vcc, 0, v173, vcc
	v_add_co_u32_e32 v60, vcc, 0x15546000, v170
	global_load_dwordx4 v[56:59], v[56:57], off
	s_nop 0
	v_addc_co_u32_e32 v61, vcc, 0, v171, vcc
	v_add_co_u32_e32 v64, vcc, 0x15546000, v168
	global_load_dwordx4 v[60:63], v[60:61], off
	s_nop 0
	v_addc_co_u32_e32 v65, vcc, 0, v169, vcc
	v_add_co_u32_e32 v68, vcc, 0x15546000, v166
	global_load_dwordx4 v[64:67], v[64:65], off
	s_nop 0
	v_addc_co_u32_e32 v69, vcc, 0, v167, vcc
	v_add_co_u32_e32 v72, vcc, 0x15546000, v164
	global_load_dwordx4 v[68:71], v[68:69], off
	s_nop 0
	v_addc_co_u32_e32 v73, vcc, 0, v165, vcc
	v_add_co_u32_e32 v76, vcc, 0x15546000, v160
	global_load_dwordx4 v[72:75], v[72:73], off
	s_nop 0
	v_addc_co_u32_e32 v77, vcc, 0, v161, vcc
	v_add_co_u32_e32 v80, vcc, 0x15546000, v158
	global_load_dwordx4 v[76:79], v[76:77], off
	s_nop 0
	v_addc_co_u32_e32 v81, vcc, 0, v159, vcc
	v_add_co_u32_e32 v84, vcc, 0x15546000, v156
	global_load_dwordx4 v[80:83], v[80:81], off
	s_nop 0
	v_addc_co_u32_e32 v85, vcc, 0, v157, vcc
	v_add_co_u32_e32 v88, vcc, 0x15546000, v154
	global_load_dwordx4 v[84:87], v[84:85], off
	s_nop 0
	v_addc_co_u32_e32 v89, vcc, 0, v155, vcc
	v_add_co_u32_e32 v92, vcc, 0x15546000, v152
	global_load_dwordx4 v[88:91], v[88:89], off
	s_nop 0
	v_addc_co_u32_e32 v93, vcc, 0, v153, vcc
	v_add_co_u32_e32 v96, vcc, 0x15546000, v150
	global_load_dwordx4 v[92:95], v[92:93], off
	s_nop 0
	v_addc_co_u32_e32 v97, vcc, 0, v151, vcc
	v_add_co_u32_e32 v100, vcc, 0x15546000, v148
	global_load_dwordx4 v[96:99], v[96:97], off
	s_nop 0
	v_addc_co_u32_e32 v101, vcc, 0, v149, vcc
	v_add_co_u32_e32 v104, vcc, 0x15546000, v146
	global_load_dwordx4 v[100:103], v[100:101], off
	s_nop 0
	v_addc_co_u32_e32 v105, vcc, 0, v147, vcc
	v_add_co_u32_e32 v108, vcc, 0x15546000, v144
	global_load_dwordx4 v[104:107], v[104:105], off
	s_nop 0
	v_addc_co_u32_e32 v109, vcc, 0, v145, vcc
	global_load_dwordx4 v[108:111], v[108:109], off
	s_setprio 0
	s_and_b64 vcc, exec, s[0:1]
	s_cbranch_vccnz .Lldr_odd_A27
	s_waitcnt vmcnt(31)
	ds_write_b128 v174, v[0:3]
	s_waitcnt vmcnt(30)
	ds_write_b128 v174, v[4:7] offset:4096
	s_waitcnt vmcnt(29)
	ds_write_b128 v174, v[8:11] offset:8192
	s_waitcnt vmcnt(28)
	ds_write_b128 v174, v[12:15] offset:12288
	s_waitcnt vmcnt(27)
	ds_write_b128 v174, v[16:19] offset:16384
	s_waitcnt vmcnt(26)
	ds_write_b128 v174, v[20:23] offset:20480
	s_waitcnt vmcnt(25)
	ds_write_b128 v174, v[24:27] offset:24576
	s_waitcnt vmcnt(24)
	ds_write_b128 v174, v[28:31] offset:28672
	s_waitcnt vmcnt(23)
	ds_write_b128 v174, v[32:35] offset:32768
	s_waitcnt vmcnt(22)
	ds_write_b128 v174, v[36:39] offset:36864
	s_waitcnt vmcnt(21)
	ds_write_b128 v174, v[40:43] offset:40960
	s_waitcnt vmcnt(20)
	ds_write_b128 v174, v[44:47] offset:45056
	s_waitcnt vmcnt(19)
	ds_write_b128 v174, v[48:51] offset:49152
	s_waitcnt vmcnt(18)
	ds_write_b128 v174, v[52:55] offset:53248
	s_branch .Lldr_odd_wr_done
